# GEMM K-loop: the per-block s_setprio toggles removed
# speedup vs baseline: 1.0075x; 1.0071x over previous
.LBB0_463:
	v_or_b32_e32 v136, 0x10000, v238
	v_add_u32_e32 v140, 0x10400, v238
	v_add_u32_e32 v144, 0x10800, v238
	v_add_u32_e32 v148, 0x10c00, v238
	v_or_b32_e32 v152, 0x14000, v238
	v_add_u32_e32 v156, 0x14400, v238
	v_add_u32_e32 v160, 0x14800, v238
	v_add_u32_e32 v164, 0x14c00, v238
	s_add_i32 s9, s6, 2
	s_waitcnt lgkmcnt(0)
	ds_read_b128 v[136:139], v136
	ds_read_b128 v[140:143], v140
	ds_read_b128 v[144:147], v144
	ds_read_b128 v[148:151], v148
	ds_read_b128 v[152:155], v152
	ds_read_b128 v[156:159], v156
	ds_read_b128 v[160:163], v160
	ds_read_b128 v[164:167], v164
	s_add_u32 s10, s4, 0x80
	s_addc_u32 s7, s5, 0
	s_cmp_eq_u32 s94, s6
	s_cselect_b32 s6, s62, s10
	s_cselect_b32 s7, s63, s7
	s_cselect_b32 s11, s65, s8
	s_cselect_b32 s10, s64, s3
	v_lshl_add_u64 v[172:173], s[4:5], 0, v[182:183]
	s_add_i32 m0, s35, 0xc000
	ds_read_b128 v[168:171], v237
	ds_read_b128 v[186:189], v237 offset:1024
	ds_read_b128 v[190:193], v237 offset:2048
	ds_read_b128 v[194:197], v237 offset:3072
	ds_read_b128 v[198:201], v237 offset:4096
	ds_read_b128 v[202:205], v237 offset:5120
	ds_read_b128 v[206:209], v237 offset:6144
	ds_read_b128 v[240:243], v237 offset:7168
	global_load_lds_dwordx4 v[172:173], off
	v_lshl_add_u64 v[172:173], s[4:5], 0, v[184:185]
	s_add_i32 m0, s35, 0xe000
	s_nop 0
	global_load_lds_dwordx4 v[172:173], off
	s_waitcnt vmcnt(8)
	s_waitcnt lgkmcnt(0)
	s_barrier
	s_waitcnt lgkmcnt(0)
	v_mfma_f32_16x16x32_bf16 v[132:135], v[136:139], v[168:171], v[132:135]
	v_mfma_f32_16x16x32_bf16 v[128:131], v[144:147], v[168:171], v[128:131]
	v_mfma_f32_16x16x32_bf16 v[116:119], v[136:139], v[190:193], v[116:119]
	v_mfma_f32_16x16x32_bf16 v[106:109], v[144:147], v[190:193], v[106:109]
	v_mfma_f32_16x16x32_bf16 v[94:97], v[136:139], v[198:201], v[94:97]
	v_mfma_f32_16x16x32_bf16 v[90:93], v[144:147], v[198:201], v[90:93]
	v_mfma_f32_16x16x32_bf16 v[78:81], v[136:139], v[206:209], v[78:81]
	v_mfma_f32_16x16x32_bf16 v[74:77], v[144:147], v[206:209], v[74:77]
	v_mfma_f32_16x16x32_bf16 v[132:135], v[140:143], v[186:189], v[132:135]
	v_mfma_f32_16x16x32_bf16 v[128:131], v[148:151], v[186:189], v[128:131]
	v_mfma_f32_16x16x32_bf16 v[116:119], v[140:143], v[194:197], v[116:119]
	v_mfma_f32_16x16x32_bf16 v[106:109], v[148:151], v[194:197], v[106:109]
	v_mfma_f32_16x16x32_bf16 v[94:97], v[140:143], v[202:205], v[94:97]
	v_mfma_f32_16x16x32_bf16 v[90:93], v[148:151], v[202:205], v[90:93]
	v_mfma_f32_16x16x32_bf16 v[78:81], v[140:143], v[240:243], v[78:81]
	v_mfma_f32_16x16x32_bf16 v[74:77], v[148:151], v[240:243], v[74:77]
	v_mfma_f32_16x16x32_bf16 v[124:127], v[152:155], v[168:171], v[124:127]
	v_mfma_f32_16x16x32_bf16 v[120:123], v[160:163], v[168:171], v[120:123]
	v_mfma_f32_16x16x32_bf16 v[102:105], v[152:155], v[190:193], v[102:105]
	v_mfma_f32_16x16x32_bf16 v[98:101], v[160:163], v[190:193], v[98:101]
	v_mfma_f32_16x16x32_bf16 v[86:89], v[152:155], v[198:201], v[86:89]
	v_mfma_f32_16x16x32_bf16 v[82:85], v[160:163], v[198:201], v[82:85]
	v_mfma_f32_16x16x32_bf16 v[70:73], v[152:155], v[206:209], v[70:73]
	v_mfma_f32_16x16x32_bf16 v[66:69], v[160:163], v[206:209], v[66:69]
	v_mfma_f32_16x16x32_bf16 v[124:127], v[156:159], v[186:189], v[124:127]
	v_mfma_f32_16x16x32_bf16 v[120:123], v[164:167], v[186:189], v[120:123]
	v_mfma_f32_16x16x32_bf16 v[102:105], v[156:159], v[194:197], v[102:105]
	v_mfma_f32_16x16x32_bf16 v[98:101], v[164:167], v[194:197], v[98:101]
	v_mfma_f32_16x16x32_bf16 v[86:89], v[156:159], v[202:205], v[86:89]
	v_mfma_f32_16x16x32_bf16 v[82:85], v[164:167], v[202:205], v[82:85]
	v_mfma_f32_16x16x32_bf16 v[70:73], v[156:159], v[240:243], v[70:73]
	v_mfma_f32_16x16x32_bf16 v[66:69], v[164:167], v[240:243], v[66:69]
	s_barrier
	s_mov_b32 m0, s78
	v_lshl_add_u64 v[172:173], s[10:11], 0, v[180:181]
	v_lshl_add_u64 v[210:211], s[10:11], 0, v[176:177]
	s_add_u32 s10, s10, s24
	ds_read_b128 v[168:171], v237 offset:16384
	ds_read_b128 v[186:189], v237 offset:17408
	ds_read_b128 v[190:193], v237 offset:18432
	ds_read_b128 v[194:197], v237 offset:19456
	ds_read_b128 v[198:201], v237 offset:20480
	ds_read_b128 v[202:205], v237 offset:21504
	ds_read_b128 v[206:209], v237 offset:22528
	ds_read_b128 v[240:243], v237 offset:23552
	global_load_lds_dwordx4 v[172:173], off
	s_mov_b32 m0, s79
	s_addc_u32 s11, s11, s25
	global_load_lds_dwordx4 v[210:211], off
	v_lshl_add_u64 v[244:245], s[10:11], 0, v[180:181]
	s_mov_b32 m0, s80
	v_lshl_add_u64 v[246:247], s[10:11], 0, v[176:177]
	global_load_lds_dwordx4 v[244:245], off
	s_mov_b32 m0, s81
	v_lshl_add_u64 v[248:249], s[6:7], 0, v[178:179]
	global_load_lds_dwordx4 v[246:247], off
	s_mov_b32 m0, s35
	v_lshl_add_u64 v[250:251], s[6:7], 0, v[110:111]
	global_load_lds_dwordx4 v[248:249], off
	s_mov_b32 m0, s82
	s_nop 0
	global_load_lds_dwordx4 v[250:251], off
	s_waitcnt vmcnt(8)
	s_waitcnt lgkmcnt(0)
	s_barrier
	s_waitcnt lgkmcnt(0)
	v_mfma_f32_16x16x32_bf16 v[62:65], v[136:139], v[168:171], v[62:65]
	v_mfma_f32_16x16x32_bf16 v[58:61], v[144:147], v[168:171], v[58:61]
	v_mfma_f32_16x16x32_bf16 v[46:49], v[136:139], v[190:193], v[46:49]
	v_mfma_f32_16x16x32_bf16 v[42:45], v[144:147], v[190:193], v[42:45]
	v_mfma_f32_16x16x32_bf16 v[30:33], v[136:139], v[198:201], v[30:33]
	v_mfma_f32_16x16x32_bf16 v[26:29], v[144:147], v[198:201], v[26:29]
	v_mfma_f32_16x16x32_bf16 v[14:17], v[136:139], v[206:209], v[14:17]
	v_mfma_f32_16x16x32_bf16 v[10:13], v[144:147], v[206:209], v[10:13]
	v_mfma_f32_16x16x32_bf16 v[62:65], v[140:143], v[186:189], v[62:65]
	v_mfma_f32_16x16x32_bf16 v[58:61], v[148:151], v[186:189], v[58:61]
	v_mfma_f32_16x16x32_bf16 v[46:49], v[140:143], v[194:197], v[46:49]
	v_mfma_f32_16x16x32_bf16 v[42:45], v[148:151], v[194:197], v[42:45]
	v_mfma_f32_16x16x32_bf16 v[30:33], v[140:143], v[202:205], v[30:33]
	v_mfma_f32_16x16x32_bf16 v[26:29], v[148:151], v[202:205], v[26:29]
	v_mfma_f32_16x16x32_bf16 v[14:17], v[140:143], v[240:243], v[14:17]
	v_mfma_f32_16x16x32_bf16 v[10:13], v[148:151], v[240:243], v[10:13]
	v_mfma_f32_16x16x32_bf16 v[54:57], v[152:155], v[168:171], v[54:57]
	v_mfma_f32_16x16x32_bf16 v[50:53], v[160:163], v[168:171], v[50:53]
	v_mfma_f32_16x16x32_bf16 v[38:41], v[152:155], v[190:193], v[38:41]
	v_mfma_f32_16x16x32_bf16 v[34:37], v[160:163], v[190:193], v[34:37]
	v_mfma_f32_16x16x32_bf16 v[22:25], v[152:155], v[198:201], v[22:25]
	v_mfma_f32_16x16x32_bf16 v[18:21], v[160:163], v[198:201], v[18:21]
	v_mfma_f32_16x16x32_bf16 v[6:9], v[152:155], v[206:209], v[6:9]
	v_mfma_f32_16x16x32_bf16 v[2:5], v[160:163], v[206:209], v[2:5]
	v_mfma_f32_16x16x32_bf16 v[54:57], v[156:159], v[186:189], v[54:57]
	v_mfma_f32_16x16x32_bf16 v[50:53], v[164:167], v[186:189], v[50:53]
	v_mfma_f32_16x16x32_bf16 v[38:41], v[156:159], v[194:197], v[38:41]
	v_mfma_f32_16x16x32_bf16 v[34:37], v[164:167], v[194:197], v[34:37]
	v_mfma_f32_16x16x32_bf16 v[22:25], v[156:159], v[202:205], v[22:25]
	v_mfma_f32_16x16x32_bf16 v[18:21], v[164:167], v[202:205], v[18:21]
	v_mfma_f32_16x16x32_bf16 v[6:9], v[156:159], v[240:243], v[6:9]
	v_mfma_f32_16x16x32_bf16 v[2:5], v[164:167], v[240:243], v[2:5]
	s_barrier
	v_or_b32_e32 v136, 0x18000, v238
	v_add_u32_e32 v140, 0x18400, v238
	v_add_u32_e32 v144, 0x18800, v238
	v_add_u32_e32 v148, 0x18c00, v238
	v_or_b32_e32 v152, 0x1c000, v238
	v_add_u32_e32 v156, 0x1c400, v238
	v_add_u32_e32 v160, 0x1c800, v238
	v_add_u32_e32 v164, 0x1cc00, v238
	ds_read_b128 v[136:139], v136
	ds_read_b128 v[140:143], v140
	ds_read_b128 v[144:147], v144
	ds_read_b128 v[148:151], v148
	ds_read_b128 v[152:155], v152
	ds_read_b128 v[156:159], v156
	ds_read_b128 v[160:163], v160
	ds_read_b128 v[164:167], v164
	s_add_u32 s6, s6, s26
	s_addc_u32 s7, s7, s27
	s_mov_b32 m0, s83
	v_lshl_add_u64 v[212:213], s[6:7], 0, v[178:179]
	ds_read_b128 v[168:171], v237 offset:32768
	ds_read_b128 v[186:189], v237 offset:33792
	ds_read_b128 v[190:193], v237 offset:34816
	ds_read_b128 v[194:197], v237 offset:35840
	ds_read_b128 v[198:201], v237 offset:36864
	ds_read_b128 v[202:205], v237 offset:37888
	ds_read_b128 v[206:209], v237 offset:38912
	ds_read_b128 v[240:243], v237 offset:39936
	global_load_lds_dwordx4 v[212:213], off
	v_lshl_add_u64 v[212:213], s[6:7], 0, v[110:111]
	s_mov_b32 m0, s84
	s_nop 0
	global_load_lds_dwordx4 v[212:213], off
	s_waitcnt vmcnt(8)
	s_waitcnt lgkmcnt(0)
	s_barrier
	s_waitcnt lgkmcnt(0)
	v_mfma_f32_16x16x32_bf16 v[132:135], v[136:139], v[168:171], v[132:135]
	v_mfma_f32_16x16x32_bf16 v[128:131], v[144:147], v[168:171], v[128:131]
	v_mfma_f32_16x16x32_bf16 v[116:119], v[136:139], v[190:193], v[116:119]
	v_mfma_f32_16x16x32_bf16 v[106:109], v[144:147], v[190:193], v[106:109]
	v_mfma_f32_16x16x32_bf16 v[94:97], v[136:139], v[198:201], v[94:97]
	v_mfma_f32_16x16x32_bf16 v[90:93], v[144:147], v[198:201], v[90:93]
	v_mfma_f32_16x16x32_bf16 v[78:81], v[136:139], v[206:209], v[78:81]
	v_mfma_f32_16x16x32_bf16 v[74:77], v[144:147], v[206:209], v[74:77]
	v_mfma_f32_16x16x32_bf16 v[132:135], v[140:143], v[186:189], v[132:135]
	v_mfma_f32_16x16x32_bf16 v[128:131], v[148:151], v[186:189], v[128:131]
	v_mfma_f32_16x16x32_bf16 v[116:119], v[140:143], v[194:197], v[116:119]
	v_mfma_f32_16x16x32_bf16 v[106:109], v[148:151], v[194:197], v[106:109]
	v_mfma_f32_16x16x32_bf16 v[94:97], v[140:143], v[202:205], v[94:97]
	v_mfma_f32_16x16x32_bf16 v[90:93], v[148:151], v[202:205], v[90:93]
	v_mfma_f32_16x16x32_bf16 v[78:81], v[140:143], v[240:243], v[78:81]
	v_mfma_f32_16x16x32_bf16 v[74:77], v[148:151], v[240:243], v[74:77]
	v_mfma_f32_16x16x32_bf16 v[124:127], v[152:155], v[168:171], v[124:127]
	v_mfma_f32_16x16x32_bf16 v[120:123], v[160:163], v[168:171], v[120:123]
	v_mfma_f32_16x16x32_bf16 v[102:105], v[152:155], v[190:193], v[102:105]
	v_mfma_f32_16x16x32_bf16 v[98:101], v[160:163], v[190:193], v[98:101]
	v_mfma_f32_16x16x32_bf16 v[86:89], v[152:155], v[198:201], v[86:89]
	v_mfma_f32_16x16x32_bf16 v[82:85], v[160:163], v[198:201], v[82:85]
	v_mfma_f32_16x16x32_bf16 v[70:73], v[152:155], v[206:209], v[70:73]
	v_mfma_f32_16x16x32_bf16 v[66:69], v[160:163], v[206:209], v[66:69]
	v_mfma_f32_16x16x32_bf16 v[124:127], v[156:159], v[186:189], v[124:127]
	v_mfma_f32_16x16x32_bf16 v[120:123], v[164:167], v[186:189], v[120:123]
	v_mfma_f32_16x16x32_bf16 v[102:105], v[156:159], v[194:197], v[102:105]
	v_mfma_f32_16x16x32_bf16 v[98:101], v[164:167], v[194:197], v[98:101]
	v_mfma_f32_16x16x32_bf16 v[86:89], v[156:159], v[202:205], v[86:89]
	v_mfma_f32_16x16x32_bf16 v[82:85], v[164:167], v[202:205], v[82:85]
	v_mfma_f32_16x16x32_bf16 v[70:73], v[156:159], v[240:243], v[70:73]
	v_mfma_f32_16x16x32_bf16 v[66:69], v[164:167], v[240:243], v[66:69]
	s_barrier
	s_mov_b32 m0, s88
	v_lshl_add_u64 v[172:173], v[172:173], 0, s[0:1]
	ds_read_b128 v[168:171], v237 offset:49152
	ds_read_b128 v[186:189], v237 offset:50176
	ds_read_b128 v[190:193], v237 offset:51200
	ds_read_b128 v[194:197], v237 offset:52224
	ds_read_b128 v[198:201], v237 offset:53248
	ds_read_b128 v[202:205], v237 offset:54272
	ds_read_b128 v[206:209], v237 offset:55296
	ds_read_b128 v[240:243], v237 offset:56320
	global_load_lds_dwordx4 v[172:173], off
	v_lshl_add_u64 v[172:173], v[210:211], 0, s[0:1]
	s_mov_b32 m0, s89
	s_nop 0
	global_load_lds_dwordx4 v[172:173], off
	v_lshl_add_u64 v[172:173], v[244:245], 0, s[0:1]
	s_mov_b32 m0, s92
	s_nop 0
	global_load_lds_dwordx4 v[172:173], off
	v_lshl_add_u64 v[172:173], v[246:247], 0, s[0:1]
	s_mov_b32 m0, s93
	s_nop 0
	global_load_lds_dwordx4 v[172:173], off
	v_lshl_add_u64 v[172:173], v[248:249], 0, s[0:1]
	s_mov_b32 m0, s90
	s_nop 0
	global_load_lds_dwordx4 v[172:173], off
	v_lshl_add_u64 v[172:173], v[250:251], 0, s[0:1]
	s_mov_b32 m0, s91
	s_nop 0
	global_load_lds_dwordx4 v[172:173], off
	s_waitcnt vmcnt(8)
	s_waitcnt lgkmcnt(0)
	s_barrier
	s_waitcnt lgkmcnt(0)
	v_mfma_f32_16x16x32_bf16 v[62:65], v[136:139], v[168:171], v[62:65]
	v_mfma_f32_16x16x32_bf16 v[58:61], v[144:147], v[168:171], v[58:61]
	v_mfma_f32_16x16x32_bf16 v[46:49], v[136:139], v[190:193], v[46:49]
	v_mfma_f32_16x16x32_bf16 v[42:45], v[144:147], v[190:193], v[42:45]
	v_mfma_f32_16x16x32_bf16 v[30:33], v[136:139], v[198:201], v[30:33]
	v_mfma_f32_16x16x32_bf16 v[26:29], v[144:147], v[198:201], v[26:29]
	v_mfma_f32_16x16x32_bf16 v[14:17], v[136:139], v[206:209], v[14:17]
	v_mfma_f32_16x16x32_bf16 v[10:13], v[144:147], v[206:209], v[10:13]
	v_mfma_f32_16x16x32_bf16 v[62:65], v[140:143], v[186:189], v[62:65]
	v_mfma_f32_16x16x32_bf16 v[58:61], v[148:151], v[186:189], v[58:61]
	v_mfma_f32_16x16x32_bf16 v[46:49], v[140:143], v[194:197], v[46:49]
	v_mfma_f32_16x16x32_bf16 v[42:45], v[148:151], v[194:197], v[42:45]
	v_mfma_f32_16x16x32_bf16 v[30:33], v[140:143], v[202:205], v[30:33]
	v_mfma_f32_16x16x32_bf16 v[26:29], v[148:151], v[202:205], v[26:29]
	v_mfma_f32_16x16x32_bf16 v[14:17], v[140:143], v[240:243], v[14:17]
	v_mfma_f32_16x16x32_bf16 v[10:13], v[148:151], v[240:243], v[10:13]
	v_mfma_f32_16x16x32_bf16 v[54:57], v[152:155], v[168:171], v[54:57]
	v_mfma_f32_16x16x32_bf16 v[50:53], v[160:163], v[168:171], v[50:53]
	v_mfma_f32_16x16x32_bf16 v[38:41], v[152:155], v[190:193], v[38:41]
	v_mfma_f32_16x16x32_bf16 v[34:37], v[160:163], v[190:193], v[34:37]
	v_mfma_f32_16x16x32_bf16 v[22:25], v[152:155], v[198:201], v[22:25]
	v_mfma_f32_16x16x32_bf16 v[18:21], v[160:163], v[198:201], v[18:21]
	v_mfma_f32_16x16x32_bf16 v[6:9], v[152:155], v[206:209], v[6:9]
	v_mfma_f32_16x16x32_bf16 v[2:5], v[160:163], v[206:209], v[2:5]
	v_mfma_f32_16x16x32_bf16 v[54:57], v[156:159], v[186:189], v[54:57]
	v_mfma_f32_16x16x32_bf16 v[50:53], v[164:167], v[186:189], v[50:53]
	v_mfma_f32_16x16x32_bf16 v[38:41], v[156:159], v[194:197], v[38:41]
	v_mfma_f32_16x16x32_bf16 v[34:37], v[164:167], v[194:197], v[34:37]
	v_mfma_f32_16x16x32_bf16 v[22:25], v[156:159], v[202:205], v[22:25]
	v_mfma_f32_16x16x32_bf16 v[18:21], v[164:167], v[202:205], v[18:21]
	v_mfma_f32_16x16x32_bf16 v[6:9], v[156:159], v[240:243], v[6:9]
	v_mfma_f32_16x16x32_bf16 v[2:5], v[164:167], v[240:243], v[2:5]
	s_barrier
	s_add_u32 s4, s4, 0x100
	s_addc_u32 s5, s5, 0
	s_add_u32 s3, s3, 0x100
	s_addc_u32 s8, s8, 0
	s_cmp_ge_u32 s9, s85
	s_mov_b32 s6, s9
	s_cbranch_scc0 .LBB0_463
	s_and_b64 vcc, exec, s[58:59]
	s_cbranch_vccz .LBB0_466
	s_barrier
